# step-0 barrier uses the same XCD-hierarchical barrier as the other steps instead of cooperative-groups grid.sync
# baseline (speedup 1.0000x reference)
; __global__ void __launch_bounds__(512, 2) hybrid_fwd(Args args) {
;     ...
;         if (st + 1 < NSTEPS) { if (st == 0) grid.sync(); else xcd_barrier(xbar); }
.LBB0_948:
	s_cmp_lg_u32 s36, -1
	s_mov_b64 s[2:3], -1
	s_cselect_b64 s[4:5], -1, 0
	s_andn2_b64 vcc, exec, s[4:5]
	s_mov_b64 s[4:5], 0
	s_cbranch_vccz .LBB0_936
